# out-proj epilogue: the f32 residual-stream stores (re-read only one layer later) carry nt, so they do not displace the bf16/fp8 activations the next in-proj reads
# baseline (speedup 1.0000x reference)
.LBB0_1643:
	v_lshl_add_u32 v212, s92, 8, v227
	v_lshl_or_b32 v122, s93, 8, v229
	v_ashrrev_i32_e32 v213, 31, v212
	v_lshlrev_b64 v[124:125], 10, v[212:213]
	v_ashrrev_i32_e32 v123, 31, v122
	v_lshl_add_u64 v[206:207], v[124:125], 0, v[122:123]
	v_lshlrev_b64 v[194:195], 2, v[206:207]
	v_lshl_add_u64 v[210:211], s[18:19], 0, v[194:195]
	s_mov_b64 s[8:9], 0x10000
	v_lshl_add_u64 v[122:123], v[210:211], 0, s[8:9]
	s_mov_b32 s8, 0x10000
	v_add_co_u32_e32 v124, vcc, s8, v210
	s_mov_b64 s[8:9], 0x10200
	s_nop 0
	v_addc_co_u32_e32 v125, vcc, 0, v211, vcc
	global_load_dwordx4 v[186:189], v[210:211], off offset:16
	global_load_dwordx4 v[190:193], v[210:211], off
	global_load_dwordx4 v[178:181], v[210:211], off offset:528
	global_load_dwordx4 v[182:185], v[210:211], off offset:512
	global_load_dwordx4 v[174:177], v[124:125], off
	global_load_dwordx4 v[170:173], v[122:123], off offset:16
	v_lshl_add_u64 v[122:123], v[210:211], 0, s[8:9]
	s_mov_b64 s[8:9], 0x20000
	global_load_dwordx4 v[166:169], v[124:125], off offset:512
	global_load_dwordx4 v[162:165], v[122:123], off offset:16
	v_lshl_add_u64 v[122:123], v[210:211], 0, s[8:9]
	s_mov_b32 s8, 0x20000
	v_add_co_u32_e32 v124, vcc, s8, v210
	s_mov_b64 s[8:9], 0x20200
	s_nop 0
	v_addc_co_u32_e32 v125, vcc, 0, v211, vcc
	global_load_dwordx4 v[158:161], v[124:125], off
	global_load_dwordx4 v[154:157], v[122:123], off offset:16
	v_lshl_add_u64 v[122:123], v[210:211], 0, s[8:9]
	s_mov_b64 s[8:9], 0x30000
	global_load_dwordx4 v[150:153], v[124:125], off offset:512
	global_load_dwordx4 v[146:149], v[122:123], off offset:16
	v_lshl_add_u64 v[122:123], v[210:211], 0, s[8:9]
	s_mov_b32 s8, 0x30000
	v_add_co_u32_e32 v124, vcc, s8, v210
	s_mov_b64 s[8:9], 0x30200
	s_nop 0
	v_addc_co_u32_e32 v125, vcc, 0, v211, vcc
	global_load_dwordx4 v[142:145], v[124:125], off
	global_load_dwordx4 v[138:141], v[122:123], off offset:16
	v_lshl_add_u64 v[122:123], v[210:211], 0, s[8:9]
	global_load_dwordx4 v[134:137], v[124:125], off offset:512
	s_nop 0
	global_load_dwordx4 v[122:125], v[122:123], off offset:16
	v_readlane_b32 s48, v251, 4
	v_cndmask_b32_e64 v208, 0, 1, s[30:31]
	v_readlane_b32 s62, v251, 18
	v_readlane_b32 s63, v251, 19
	v_cmp_ne_u32_e64 s[14:15], 1, v208
	s_andn2_b64 vcc, exec, s[30:31]
	v_lshl_add_u64 v[208:209], s[62:63], 0, v[194:195]
	v_lshl_add_u64 v[214:215], s[40:41], 0, v[206:207]
	v_lshl_add_u64 v[216:217], v[206:207], 1, s[36:37]
	v_readlane_b32 s95, v254, 58
	s_mov_b32 s94, 0xfffff
	v_readlane_b32 s49, v251, 5
	v_readlane_b32 s50, v251, 6
	v_readlane_b32 s51, v251, 7
	v_readlane_b32 s52, v251, 8
	v_readlane_b32 s53, v251, 9
	v_readlane_b32 s54, v251, 10
	v_readlane_b32 s55, v251, 11
	v_readlane_b32 s56, v251, 12
	v_readlane_b32 s57, v251, 13
	v_readlane_b32 s58, v251, 14
	v_readlane_b32 s59, v251, 15
	v_readlane_b32 s60, v251, 16
	v_readlane_b32 s61, v251, 17
	s_waitcnt vmcnt(0)
	v_pk_add_f32 v[128:129], v[128:129], v[188:189]
	v_pk_add_f32 v[132:133], v[132:133], v[192:193]
	v_pk_add_f32 v[130:131], v[130:131], v[190:191]
	v_pk_add_f32 v[126:127], v[126:127], v[186:187]
	global_store_dwordx4 v[208:209], v[130:133], off nt
	global_store_dwordx4 v[208:209], v[126:129], off offset:16 nt
	v_cvt_pk_bf16_f32 v186, v130, v131
	v_cvt_pk_bf16_f32 v187, v132, v133
	v_cvt_pk_bf16_f32 v188, v126, v127
	v_cvt_pk_bf16_f32 v189, v128, v129
	s_cbranch_vccnz .LBB0_1645
	global_store_dwordx4 v[216:217], v[186:189], off
	s_nop 1
	v_mov_b32_e32 v186, v33
	v_mov_b32_e32 v187, v33
	v_cvt_pk_fp8_f32 v186, v130, v131
	v_cvt_pk_fp8_f32 v187, v126, v127
	v_cvt_pk_fp8_f32 v186, v132, v133 op_sel:[0,0,1]
	v_cvt_pk_fp8_f32 v187, v128, v129 op_sel:[0,0,1]
	global_store_dwordx2 v[214:215], v[186:187], off
.LBB0_1645:
	v_pk_add_f32 v[120:121], v[120:121], v[184:185]
	v_pk_add_f32 v[118:119], v[118:119], v[182:183]
	v_pk_add_f32 v[116:117], v[116:117], v[180:181]
	v_pk_add_f32 v[114:115], v[114:115], v[178:179]
	s_and_b64 vcc, exec, s[14:15]
	global_store_dwordx4 v[208:209], v[118:121], off offset:512 nt
	global_store_dwordx4 v[208:209], v[114:117], off offset:528 nt
	v_cvt_pk_bf16_f32 v178, v118, v119
	v_cvt_pk_bf16_f32 v179, v120, v121
	v_cvt_pk_bf16_f32 v180, v114, v115
	v_cvt_pk_bf16_f32 v181, v116, v117
	s_cbranch_vccnz .LBB0_1647
	global_store_dwordx4 v[216:217], v[178:181], off offset:256
	s_nop 1
	v_mov_b32_e32 v178, v33
	v_mov_b32_e32 v179, v33
	v_cvt_pk_fp8_f32 v178, v118, v119
	v_cvt_pk_fp8_f32 v179, v114, v115
	v_cvt_pk_fp8_f32 v178, v120, v121 op_sel:[0,0,1]
	v_cvt_pk_fp8_f32 v179, v116, v117 op_sel:[0,0,1]
	global_store_dwordx2 v[214:215], v[178:179], off offset:128

.LBB0_1649:
	s_or_b64 exec, exec, s[74:75]
	s_mov_b64 s[8:9], 0x80000
	v_add_co_u32_e32 v116, vcc, 0x80000, v210
	s_waitcnt lgkmcnt(0)
	v_lshl_add_u64 v[114:115], v[210:211], 0, s[8:9]
	v_addc_co_u32_e32 v117, vcc, 0, v211, vcc
	s_mov_b64 s[8:9], 0x80200
	global_load_dwordx4 v[130:133], v[116:117], off
	global_load_dwordx4 v[126:129], v[114:115], off offset:16
	v_lshl_add_u64 v[114:115], v[210:211], 0, s[8:9]
	global_load_dwordx4 v[118:121], v[116:117], off offset:512
	s_nop 0
	global_load_dwordx4 v[114:117], v[114:115], off offset:16
	s_mov_b64 s[8:9], 0x4000
	v_lshl_add_u64 v[180:181], v[206:207], 0, s[8:9]
	s_mov_b64 s[8:9], 0x10000
	v_pk_add_f32 v[112:113], v[112:113], v[176:177]
	v_lshl_add_u64 v[176:177], v[208:209], 0, s[8:9]
	s_mov_b32 s8, 0x10000
	v_pk_add_f32 v[106:107], v[106:107], v[170:171]
	v_add_co_u32_e32 v170, vcc, s8, v208
	v_pk_add_f32 v[110:111], v[110:111], v[174:175]
	s_nop 0
	v_addc_co_u32_e32 v171, vcc, 0, v209, vcc
	v_pk_add_f32 v[108:109], v[108:109], v[172:173]
	s_and_b64 vcc, exec, s[14:15]
	v_lshl_add_u64 v[174:175], s[40:41], 0, v[180:181]
	v_lshl_add_u64 v[180:181], v[180:181], 1, s[36:37]
	global_store_dwordx4 v[170:171], v[110:113], off nt
	global_store_dwordx4 v[176:177], v[106:109], off offset:16 nt
	v_cvt_pk_bf16_f32 v170, v110, v111
	v_cvt_pk_bf16_f32 v171, v112, v113
	v_cvt_pk_bf16_f32 v172, v106, v107
	v_cvt_pk_bf16_f32 v173, v108, v109
	s_cbranch_vccnz .LBB0_1651
	global_store_dwordx4 v[180:181], v[170:173], off
	s_nop 1
	v_mov_b32_e32 v170, v33
	v_mov_b32_e32 v171, v33
	v_cvt_pk_fp8_f32 v170, v110, v111
	v_cvt_pk_fp8_f32 v171, v106, v107
	v_cvt_pk_fp8_f32 v170, v112, v113 op_sel:[0,0,1]
	v_cvt_pk_fp8_f32 v171, v108, v109 op_sel:[0,0,1]
	global_store_dwordx2 v[174:175], v[170:171], off
.LBB0_1651:
	v_pk_add_f32 v[104:105], v[104:105], v[168:169]
	v_pk_add_f32 v[102:103], v[102:103], v[166:167]
	v_pk_add_f32 v[100:101], v[100:101], v[164:165]
	v_pk_add_f32 v[98:99], v[98:99], v[162:163]
	s_and_b64 vcc, exec, s[14:15]
	global_store_dwordx4 v[176:177], v[102:105], off offset:512 nt
	global_store_dwordx4 v[176:177], v[98:101], off offset:528 nt
	v_cvt_pk_bf16_f32 v162, v102, v103
	v_cvt_pk_bf16_f32 v163, v104, v105
	v_cvt_pk_bf16_f32 v164, v98, v99
	v_cvt_pk_bf16_f32 v165, v100, v101
	s_cbranch_vccnz .LBB0_1653
	global_store_dwordx4 v[180:181], v[162:165], off offset:256
	s_nop 1
	v_mov_b32_e32 v162, v33
	v_mov_b32_e32 v163, v33
	v_cvt_pk_fp8_f32 v162, v102, v103
	v_cvt_pk_fp8_f32 v163, v98, v99
	v_cvt_pk_fp8_f32 v162, v104, v105 op_sel:[0,0,1]
	v_cvt_pk_fp8_f32 v163, v100, v101 op_sel:[0,0,1]
	global_store_dwordx2 v[174:175], v[162:163], off offset:128

.LBB0_1655:
	s_or_b64 exec, exec, s[74:75]
	s_mov_b64 s[8:9], 0x90000
	v_add_co_u32_e32 v100, vcc, 0x90000, v210
	s_waitcnt lgkmcnt(0)
	v_lshl_add_u64 v[98:99], v[210:211], 0, s[8:9]
	v_addc_co_u32_e32 v101, vcc, 0, v211, vcc
	s_mov_b64 s[8:9], 0x90200
	global_load_dwordx4 v[110:113], v[100:101], off
	global_load_dwordx4 v[106:109], v[98:99], off offset:16
	v_lshl_add_u64 v[98:99], v[210:211], 0, s[8:9]
	global_load_dwordx4 v[102:105], v[100:101], off offset:512
	s_nop 0
	global_load_dwordx4 v[98:101], v[98:99], off offset:16
	s_mov_b64 s[8:9], 0x8000
	v_lshl_add_u64 v[162:163], v[206:207], 0, s[8:9]
	s_mov_b64 s[8:9], 0x20000
	v_pk_add_f32 v[96:97], v[96:97], v[160:161]
	v_lshl_add_u64 v[160:161], v[208:209], 0, s[8:9]
	s_mov_b32 s8, 0x20000
	v_pk_add_f32 v[90:91], v[90:91], v[154:155]
	v_add_co_u32_e32 v154, vcc, s8, v208
	v_pk_add_f32 v[94:95], v[94:95], v[158:159]
	s_nop 0
	v_addc_co_u32_e32 v155, vcc, 0, v209, vcc
	v_pk_add_f32 v[92:93], v[92:93], v[156:157]
	s_and_b64 vcc, exec, s[14:15]
	v_lshl_add_u64 v[158:159], s[40:41], 0, v[162:163]
	v_lshl_add_u64 v[162:163], v[162:163], 1, s[36:37]
	global_store_dwordx4 v[154:155], v[94:97], off nt
	global_store_dwordx4 v[160:161], v[90:93], off offset:16 nt
	v_cvt_pk_bf16_f32 v154, v94, v95
	v_cvt_pk_bf16_f32 v155, v96, v97
	v_cvt_pk_bf16_f32 v156, v90, v91
	v_cvt_pk_bf16_f32 v157, v92, v93
	s_cbranch_vccnz .LBB0_1657
	global_store_dwordx4 v[162:163], v[154:157], off
	s_nop 1
	v_mov_b32_e32 v154, v33
	v_mov_b32_e32 v155, v33
	v_cvt_pk_fp8_f32 v154, v94, v95
	v_cvt_pk_fp8_f32 v155, v90, v91
	v_cvt_pk_fp8_f32 v154, v96, v97 op_sel:[0,0,1]
	v_cvt_pk_fp8_f32 v155, v92, v93 op_sel:[0,0,1]
	global_store_dwordx2 v[158:159], v[154:155], off
.LBB0_1657:
	v_pk_add_f32 v[88:89], v[88:89], v[152:153]
	v_pk_add_f32 v[86:87], v[86:87], v[150:151]
	v_pk_add_f32 v[84:85], v[84:85], v[148:149]
	v_pk_add_f32 v[82:83], v[82:83], v[146:147]
	s_and_b64 vcc, exec, s[14:15]
	global_store_dwordx4 v[160:161], v[86:89], off offset:512 nt
	global_store_dwordx4 v[160:161], v[82:85], off offset:528 nt
	v_cvt_pk_bf16_f32 v146, v86, v87
	v_cvt_pk_bf16_f32 v147, v88, v89
	v_cvt_pk_bf16_f32 v148, v82, v83
	v_cvt_pk_bf16_f32 v149, v84, v85
	s_cbranch_vccnz .LBB0_1659
	global_store_dwordx4 v[162:163], v[146:149], off offset:256
	s_nop 1
	v_mov_b32_e32 v146, v33
	v_mov_b32_e32 v147, v33
	v_cvt_pk_fp8_f32 v146, v86, v87
	v_cvt_pk_fp8_f32 v147, v82, v83
	v_cvt_pk_fp8_f32 v146, v88, v89 op_sel:[0,0,1]
	v_cvt_pk_fp8_f32 v147, v84, v85 op_sel:[0,0,1]
	global_store_dwordx2 v[158:159], v[146:147], off offset:128

.LBB0_1661:
	s_or_b64 exec, exec, s[74:75]
	s_mov_b64 s[8:9], 0xa0000
	v_add_co_u32_e32 v84, vcc, 0xa0000, v210
	s_waitcnt lgkmcnt(0)
	v_lshl_add_u64 v[82:83], v[210:211], 0, s[8:9]
	v_addc_co_u32_e32 v85, vcc, 0, v211, vcc
	s_mov_b64 s[8:9], 0xa0200
	global_load_dwordx4 v[94:97], v[84:85], off
	global_load_dwordx4 v[90:93], v[82:83], off offset:16
	v_lshl_add_u64 v[82:83], v[210:211], 0, s[8:9]
	global_load_dwordx4 v[86:89], v[84:85], off offset:512
	s_nop 0
	global_load_dwordx4 v[82:85], v[82:83], off offset:16
	s_mov_b64 s[8:9], 0xc000
	v_lshl_add_u64 v[146:147], v[206:207], 0, s[8:9]
	s_mov_b64 s[8:9], 0x30000
	v_pk_add_f32 v[80:81], v[80:81], v[144:145]
	v_lshl_add_u64 v[144:145], v[208:209], 0, s[8:9]
	s_mov_b32 s8, 0x30000
	v_pk_add_f32 v[74:75], v[74:75], v[138:139]
	v_add_co_u32_e32 v138, vcc, s8, v208
	v_pk_add_f32 v[78:79], v[78:79], v[142:143]
	s_nop 0
	v_addc_co_u32_e32 v139, vcc, 0, v209, vcc
	v_pk_add_f32 v[76:77], v[76:77], v[140:141]
	s_and_b64 vcc, exec, s[14:15]
	v_lshl_add_u64 v[142:143], s[40:41], 0, v[146:147]
	v_lshl_add_u64 v[146:147], v[146:147], 1, s[36:37]
	global_store_dwordx4 v[138:139], v[78:81], off nt
	global_store_dwordx4 v[144:145], v[74:77], off offset:16 nt
	v_cvt_pk_bf16_f32 v138, v78, v79
	v_cvt_pk_bf16_f32 v139, v80, v81
	v_cvt_pk_bf16_f32 v140, v74, v75
	v_cvt_pk_bf16_f32 v141, v76, v77
	s_cbranch_vccnz .LBB0_1663
	global_store_dwordx4 v[146:147], v[138:141], off
	s_nop 1
	v_mov_b32_e32 v138, v33
	v_mov_b32_e32 v139, v33
	v_cvt_pk_fp8_f32 v138, v78, v79
	v_cvt_pk_fp8_f32 v139, v74, v75
	v_cvt_pk_fp8_f32 v138, v80, v81 op_sel:[0,0,1]
	v_cvt_pk_fp8_f32 v139, v76, v77 op_sel:[0,0,1]
	global_store_dwordx2 v[142:143], v[138:139], off
.LBB0_1663:
	v_pk_add_f32 v[72:73], v[72:73], v[136:137]
	v_pk_add_f32 v[70:71], v[70:71], v[134:135]
	v_pk_add_f32 v[68:69], v[68:69], v[124:125]
	v_pk_add_f32 v[66:67], v[66:67], v[122:123]
	s_and_b64 vcc, exec, s[14:15]
	global_store_dwordx4 v[144:145], v[70:73], off offset:512 nt
	global_store_dwordx4 v[144:145], v[66:69], off offset:528 nt
	v_cvt_pk_bf16_f32 v122, v70, v71
	v_cvt_pk_bf16_f32 v123, v72, v73
	v_cvt_pk_bf16_f32 v124, v66, v67
	v_cvt_pk_bf16_f32 v125, v68, v69
	s_cbranch_vccnz .LBB0_1665
	global_store_dwordx4 v[146:147], v[122:125], off offset:256
	s_nop 1
	v_mov_b32_e32 v122, v33
	v_mov_b32_e32 v123, v33
	v_cvt_pk_fp8_f32 v122, v70, v71
	v_cvt_pk_fp8_f32 v123, v66, v67
	v_cvt_pk_fp8_f32 v122, v72, v73 op_sel:[0,0,1]
	v_cvt_pk_fp8_f32 v123, v68, v69 op_sel:[0,0,1]
	global_store_dwordx2 v[142:143], v[122:123], off offset:128

.LBB0_1667:
	s_or_b64 exec, exec, s[74:75]
	s_mov_b64 s[8:9], 0xb0000
	v_add_co_u32_e32 v68, vcc, 0xb0000, v210
	s_waitcnt lgkmcnt(0)
	v_lshl_add_u64 v[66:67], v[210:211], 0, s[8:9]
	v_addc_co_u32_e32 v69, vcc, 0, v211, vcc
	s_mov_b64 s[8:9], 0xb0200
	global_load_dwordx4 v[78:81], v[68:69], off
	global_load_dwordx4 v[74:77], v[66:67], off offset:16
	v_lshl_add_u64 v[66:67], v[210:211], 0, s[8:9]
	global_load_dwordx4 v[70:73], v[68:69], off offset:512
	s_nop 0
	global_load_dwordx4 v[66:69], v[66:67], off offset:16
	s_mov_b64 s[8:9], 0x20000
	v_lshl_add_u64 v[134:135], v[206:207], 0, s[8:9]
	s_mov_b64 s[8:9], 0x80000
	s_waitcnt vmcnt(26)
	v_pk_add_f32 v[60:61], v[60:61], v[128:129]
	v_lshl_add_u64 v[128:129], v[208:209], 0, s[8:9]
	s_mov_b32 s8, 0x80000
	v_add_co_u32_e32 v122, vcc, s8, v208
	v_pk_add_f32 v[64:65], v[64:65], v[132:133]
	s_nop 0
	v_addc_co_u32_e32 v123, vcc, 0, v209, vcc
	v_pk_add_f32 v[62:63], v[62:63], v[130:131]
	v_pk_add_f32 v[58:59], v[58:59], v[126:127]
	s_and_b64 vcc, exec, s[14:15]
	v_lshl_add_u64 v[126:127], s[40:41], 0, v[134:135]
	v_lshl_add_u64 v[130:131], v[134:135], 1, s[36:37]
	global_store_dwordx4 v[122:123], v[62:65], off nt
	global_store_dwordx4 v[128:129], v[58:61], off offset:16 nt
	v_cvt_pk_bf16_f32 v122, v62, v63
	v_cvt_pk_bf16_f32 v123, v64, v65
	v_cvt_pk_bf16_f32 v124, v58, v59
	v_cvt_pk_bf16_f32 v125, v60, v61
	s_cbranch_vccnz .LBB0_1669
	global_store_dwordx4 v[130:131], v[122:125], off
	s_nop 1
	v_mov_b32_e32 v122, v33
	v_mov_b32_e32 v123, v33
	v_cvt_pk_fp8_f32 v122, v62, v63
	v_cvt_pk_fp8_f32 v123, v58, v59
	v_cvt_pk_fp8_f32 v122, v64, v65 op_sel:[0,0,1]
	v_cvt_pk_fp8_f32 v123, v60, v61 op_sel:[0,0,1]
	global_store_dwordx2 v[126:127], v[122:123], off
.LBB0_1669:
	s_waitcnt vmcnt(27)
	v_pk_add_f32 v[56:57], v[56:57], v[120:121]
	v_pk_add_f32 v[54:55], v[54:55], v[118:119]
	s_waitcnt vmcnt(26)
	v_pk_add_f32 v[52:53], v[52:53], v[116:117]
	v_pk_add_f32 v[50:51], v[50:51], v[114:115]
	s_and_b64 vcc, exec, s[14:15]
	global_store_dwordx4 v[128:129], v[54:57], off offset:512 nt
	global_store_dwordx4 v[128:129], v[50:53], off offset:528 nt
	v_cvt_pk_bf16_f32 v114, v54, v55
	v_cvt_pk_bf16_f32 v115, v56, v57
	v_cvt_pk_bf16_f32 v116, v50, v51
	v_cvt_pk_bf16_f32 v117, v52, v53
	s_cbranch_vccnz .LBB0_1671
	global_store_dwordx4 v[130:131], v[114:117], off offset:256
	s_nop 1
	v_mov_b32_e32 v114, v33
	v_mov_b32_e32 v115, v33
	v_cvt_pk_fp8_f32 v114, v54, v55
	v_cvt_pk_fp8_f32 v115, v50, v51
	v_cvt_pk_fp8_f32 v114, v56, v57 op_sel:[0,0,1]
	v_cvt_pk_fp8_f32 v115, v52, v53 op_sel:[0,0,1]
	global_store_dwordx2 v[126:127], v[114:115], off offset:128

.LBB0_1673:
	s_or_b64 exec, exec, s[74:75]
	s_mov_b64 s[8:9], 0x24000
	v_lshl_add_u64 v[58:59], v[206:207], 0, s[8:9]
	s_mov_b64 s[8:9], 0x90000
	v_lshl_add_u64 v[56:57], v[208:209], 0, s[8:9]
	s_mov_b32 s8, 0x90000
	v_add_co_u32_e32 v50, vcc, s8, v208
	s_waitcnt vmcnt(23)
	v_pk_add_f32 v[48:49], v[48:49], v[112:113]
	s_waitcnt lgkmcnt(0)
	v_addc_co_u32_e32 v51, vcc, 0, v209, vcc
	v_pk_add_f32 v[46:47], v[46:47], v[110:111]
	s_waitcnt vmcnt(22)
	v_pk_add_f32 v[44:45], v[44:45], v[108:109]
	v_pk_add_f32 v[42:43], v[42:43], v[106:107]
	s_and_b64 vcc, exec, s[14:15]
	v_lshl_add_u64 v[54:55], s[40:41], 0, v[58:59]
	v_lshl_add_u64 v[58:59], v[58:59], 1, s[36:37]
	global_store_dwordx4 v[50:51], v[46:49], off nt
	global_store_dwordx4 v[56:57], v[42:45], off offset:16 nt
	v_cvt_pk_bf16_f32 v50, v46, v47
	v_cvt_pk_bf16_f32 v51, v48, v49
	v_cvt_pk_bf16_f32 v52, v42, v43
	v_cvt_pk_bf16_f32 v53, v44, v45
	s_cbranch_vccnz .LBB0_1675
	global_store_dwordx4 v[58:59], v[50:53], off
	s_nop 1
	v_mov_b32_e32 v50, v33
	v_mov_b32_e32 v51, v33
	v_cvt_pk_fp8_f32 v50, v46, v47
	v_cvt_pk_fp8_f32 v51, v42, v43
	v_cvt_pk_fp8_f32 v50, v48, v49 op_sel:[0,0,1]
	v_cvt_pk_fp8_f32 v51, v44, v45 op_sel:[0,0,1]
	global_store_dwordx2 v[54:55], v[50:51], off
.LBB0_1675:
	s_waitcnt vmcnt(23)
	v_pk_add_f32 v[40:41], v[40:41], v[104:105]
	v_pk_add_f32 v[38:39], v[38:39], v[102:103]
	s_waitcnt vmcnt(22)
	v_pk_add_f32 v[36:37], v[36:37], v[100:101]
	v_pk_add_f32 v[34:35], v[34:35], v[98:99]
	s_and_b64 vcc, exec, s[14:15]
	global_store_dwordx4 v[56:57], v[38:41], off offset:512 nt
	global_store_dwordx4 v[56:57], v[34:37], off offset:528 nt
	v_cvt_pk_bf16_f32 v50, v38, v39
	v_cvt_pk_bf16_f32 v51, v40, v41
	v_cvt_pk_bf16_f32 v52, v34, v35
	v_cvt_pk_bf16_f32 v53, v36, v37
	s_cbranch_vccnz .LBB0_1677
	global_store_dwordx4 v[58:59], v[50:53], off offset:256
	s_nop 1
	v_mov_b32_e32 v50, v33
	v_mov_b32_e32 v51, v33
	v_cvt_pk_fp8_f32 v50, v38, v39
	v_cvt_pk_fp8_f32 v51, v34, v35
	v_cvt_pk_fp8_f32 v50, v40, v41 op_sel:[0,0,1]
	v_cvt_pk_fp8_f32 v51, v36, v37 op_sel:[0,0,1]
	global_store_dwordx2 v[54:55], v[50:51], off offset:128

.LBB0_1679:
	s_or_b64 exec, exec, s[74:75]
	s_mov_b64 s[8:9], 0x28000
	v_lshl_add_u64 v[42:43], v[206:207], 0, s[8:9]
	s_mov_b64 s[8:9], 0xa0000
	v_lshl_add_u64 v[40:41], v[208:209], 0, s[8:9]
	s_mov_b32 s8, 0xa0000
	v_add_co_u32_e32 v34, vcc, s8, v208
	s_waitcnt vmcnt(19)
	v_pk_add_f32 v[30:31], v[30:31], v[96:97]
	s_waitcnt lgkmcnt(0)
	v_addc_co_u32_e32 v35, vcc, 0, v209, vcc
	v_pk_add_f32 v[28:29], v[28:29], v[94:95]
	s_waitcnt vmcnt(18)
	v_pk_add_f32 v[26:27], v[26:27], v[92:93]
	v_pk_add_f32 v[24:25], v[24:25], v[90:91]
	s_and_b64 vcc, exec, s[14:15]
	v_lshl_add_u64 v[38:39], s[40:41], 0, v[42:43]
	v_lshl_add_u64 v[42:43], v[42:43], 1, s[36:37]
	global_store_dwordx4 v[34:35], v[28:31], off nt
	global_store_dwordx4 v[40:41], v[24:27], off offset:16 nt
	v_cvt_pk_bf16_f32 v34, v28, v29
	v_cvt_pk_bf16_f32 v35, v30, v31
	v_cvt_pk_bf16_f32 v36, v24, v25
	v_cvt_pk_bf16_f32 v37, v26, v27
	s_cbranch_vccnz .LBB0_1681
	global_store_dwordx4 v[42:43], v[34:37], off
	s_nop 1
	v_mov_b32_e32 v34, v33
	v_mov_b32_e32 v35, v33
	v_cvt_pk_fp8_f32 v34, v28, v29
	v_cvt_pk_fp8_f32 v35, v24, v25
	v_cvt_pk_fp8_f32 v34, v30, v31 op_sel:[0,0,1]
	v_cvt_pk_fp8_f32 v35, v26, v27 op_sel:[0,0,1]
	global_store_dwordx2 v[38:39], v[34:35], off
.LBB0_1681:
	s_waitcnt vmcnt(19)
	v_pk_add_f32 v[22:23], v[22:23], v[88:89]
	v_pk_add_f32 v[20:21], v[20:21], v[86:87]
	s_waitcnt vmcnt(18)
	v_pk_add_f32 v[18:19], v[18:19], v[84:85]
	v_pk_add_f32 v[16:17], v[16:17], v[82:83]
	s_and_b64 vcc, exec, s[14:15]
	global_store_dwordx4 v[40:41], v[20:23], off offset:512 nt
	global_store_dwordx4 v[40:41], v[16:19], off offset:528 nt
	v_cvt_pk_bf16_f32 v34, v20, v21
	v_cvt_pk_bf16_f32 v35, v22, v23
	v_cvt_pk_bf16_f32 v36, v16, v17
	v_cvt_pk_bf16_f32 v37, v18, v19
	s_cbranch_vccnz .LBB0_1683
	global_store_dwordx4 v[42:43], v[34:37], off offset:256
	s_nop 1
	v_mov_b32_e32 v34, v33
	v_mov_b32_e32 v35, v33
	v_cvt_pk_fp8_f32 v34, v20, v21
	v_cvt_pk_fp8_f32 v35, v16, v17
	v_cvt_pk_fp8_f32 v34, v22, v23 op_sel:[0,0,1]
	v_cvt_pk_fp8_f32 v35, v18, v19 op_sel:[0,0,1]
	global_store_dwordx2 v[38:39], v[34:35], off offset:128

.LBB0_1685:
	s_or_b64 exec, exec, s[74:75]
	s_mov_b64 s[8:9], 0x2c000
	v_lshl_add_u64 v[24:25], v[206:207], 0, s[8:9]
	s_mov_b64 s[8:9], 0xb0000
	v_lshl_add_u64 v[22:23], v[208:209], 0, s[8:9]
	s_mov_b32 s8, 0xb0000
	v_add_co_u32_e32 v16, vcc, s8, v208
	s_waitcnt vmcnt(15)
	v_pk_add_f32 v[14:15], v[14:15], v[80:81]
	s_waitcnt lgkmcnt(0)
	v_addc_co_u32_e32 v17, vcc, 0, v209, vcc
	v_pk_add_f32 v[12:13], v[12:13], v[78:79]
	s_waitcnt vmcnt(14)
	v_pk_add_f32 v[10:11], v[10:11], v[76:77]
	v_pk_add_f32 v[8:9], v[8:9], v[74:75]
	s_and_b64 vcc, exec, s[14:15]
	v_lshl_add_u64 v[20:21], s[40:41], 0, v[24:25]
	v_lshl_add_u64 v[24:25], v[24:25], 1, s[36:37]
	global_store_dwordx4 v[16:17], v[12:15], off nt
	global_store_dwordx4 v[22:23], v[8:11], off offset:16 nt
	v_cvt_pk_bf16_f32 v16, v12, v13
	v_cvt_pk_bf16_f32 v17, v14, v15
	v_cvt_pk_bf16_f32 v18, v8, v9
	v_cvt_pk_bf16_f32 v19, v10, v11
	s_cbranch_vccnz .LBB0_1687
	global_store_dwordx4 v[24:25], v[16:19], off
	s_nop 1
	v_mov_b32_e32 v16, v33
	v_mov_b32_e32 v17, v33
	v_cvt_pk_fp8_f32 v16, v12, v13
	v_cvt_pk_fp8_f32 v17, v8, v9
	v_cvt_pk_fp8_f32 v16, v14, v15 op_sel:[0,0,1]
	v_cvt_pk_fp8_f32 v17, v10, v11 op_sel:[0,0,1]
	global_store_dwordx2 v[20:21], v[16:17], off
.LBB0_1687:
	s_waitcnt vmcnt(15)
	v_pk_add_f32 v[6:7], v[6:7], v[72:73]
	v_pk_add_f32 v[4:5], v[4:5], v[70:71]
	s_waitcnt vmcnt(14)
	v_pk_add_f32 v[2:3], v[2:3], v[68:69]
	v_pk_add_f32 v[0:1], v[0:1], v[66:67]
	s_and_b64 vcc, exec, s[14:15]
	global_store_dwordx4 v[22:23], v[4:7], off offset:512 nt
	global_store_dwordx4 v[22:23], v[0:3], off offset:528 nt
	v_cvt_pk_bf16_f32 v16, v4, v5
	v_cvt_pk_bf16_f32 v17, v6, v7
	v_cvt_pk_bf16_f32 v18, v0, v1
	v_cvt_pk_bf16_f32 v19, v2, v3
	s_cbranch_vccnz .LBB0_1689
	global_store_dwordx4 v[24:25], v[16:19], off offset:256
	s_nop 1
	v_mov_b32_e32 v16, v33
	v_mov_b32_e32 v17, v33
	v_cvt_pk_fp8_f32 v16, v4, v5
	v_cvt_pk_fp8_f32 v17, v0, v1
	v_cvt_pk_fp8_f32 v16, v6, v7 op_sel:[0,0,1]
	v_cvt_pk_fp8_f32 v17, v2, v3 op_sel:[0,0,1]
	global_store_dwordx2 v[20:21], v[16:17], off offset:128
